# lora_item and lru_item staging loops: all 16 trips' loads issued up front (private registers, counted waits) instead of one load-wait-convert-write round trip per trip
# speedup vs baseline: 1.0281x; 1.0065x over previous
.LBB0_366:
	s_and_b64 vcc, exec, s[0:1]
	s_cbranch_vccz .LBB0_378
	v_mov_b32_e32 v8, v172
	s_waitcnt lgkmcnt(0)
	v_cmp_gt_i32_e32 vcc, s53, v8
	s_barrier
	s_and_saveexec_b64 s[0:1], vcc
	s_cbranch_execz .LBB0_376
	v_readlane_b32 s2, v248, 56
	v_lshlrev_b32_sdwa v148, v193, v8 dst_sel:DWORD dst_unused:UNUSED_PAD src0_sel:DWORD src1_sel:BYTE_0
	v_readlane_b32 s3, v248, 57
	s_lshl_b32 s17, s16, 4
	s_addk_i32 s17, 0xd000
	v_lshl_add_u64 v[0:1], s[2:3], 0, v[148:149]
	s_movk_i32 s2, 0x80
	v_cmp_lt_u32_sdwa s[2:3], v8, s2 src0_sel:BYTE_0 src1_sel:DWORD
	v_lshlrev_b32_sdwa v2, v175, v8 dst_sel:DWORD dst_unused:UNUSED_PAD src0_sel:DWORD src1_sel:BYTE_0
	s_mov_b64 s[4:5], 0
	v_mov_b32_e32 v3, v8
	v_mov_b32_e32 v5, s17
	s_movk_i32 s12, 0x3a00
	s_nop 0
	v_mad_i64_i32 v[6:7], s[12:13], v5, s12, v[0:1]
	s_mov_b32 s14, 0x3a00
	s_mov_b32 s15, 0
	global_load_dword v88, v[6:7], off
	v_lshl_add_u64 v[104:105], v[6:7], 0, s[14:15]
	global_load_dword v89, v[104:105], off
	v_lshl_add_u64 v[6:7], v[104:105], 0, s[14:15]
	global_load_dword v90, v[6:7], off
	v_lshl_add_u64 v[104:105], v[6:7], 0, s[14:15]
	global_load_dword v91, v[104:105], off
	v_lshl_add_u64 v[6:7], v[104:105], 0, s[14:15]
	global_load_dword v92, v[6:7], off
	v_lshl_add_u64 v[104:105], v[6:7], 0, s[14:15]
	global_load_dword v93, v[104:105], off
	v_lshl_add_u64 v[6:7], v[104:105], 0, s[14:15]
	global_load_dword v94, v[6:7], off
	v_lshl_add_u64 v[104:105], v[6:7], 0, s[14:15]
	global_load_dword v95, v[104:105], off
	v_lshl_add_u64 v[6:7], v[104:105], 0, s[14:15]
	global_load_dword v96, v[6:7], off
	v_lshl_add_u64 v[104:105], v[6:7], 0, s[14:15]
	global_load_dword v97, v[104:105], off
	v_lshl_add_u64 v[6:7], v[104:105], 0, s[14:15]
	global_load_dword v98, v[6:7], off
	v_lshl_add_u64 v[104:105], v[6:7], 0, s[14:15]
	global_load_dword v99, v[104:105], off
	v_lshl_add_u64 v[6:7], v[104:105], 0, s[14:15]
	global_load_dword v100, v[6:7], off
	v_lshl_add_u64 v[104:105], v[6:7], 0, s[14:15]
	global_load_dword v101, v[104:105], off
	v_lshl_add_u64 v[6:7], v[104:105], 0, s[14:15]
	global_load_dword v102, v[6:7], off
	v_lshl_add_u64 v[104:105], v[6:7], 0, s[14:15]
	global_load_dword v103, v[104:105], off
	v_ashrrev_i32_e32 v4, 8, v3
	s_waitcnt vmcnt(15)
	v_mov_b32_e32 v5, v88
	s_and_saveexec_b64 s[12:13], s[2:3]
	s_cbranch_execz .Llst370_0
	s_mov_b32 s14, 0x3f200000
	v_cmp_nlt_f32_e64 s[14:15], |v5|, s14
	s_and_saveexec_b64 s[18:19], s[14:15]
	s_xor_b64 s[14:15], exec, s[18:19]
	s_cbranch_execz .Llst374_0
	v_add_f32_e64 v6, |v5|, |v5|
	v_mul_f32_e32 v7, 0x3fb8aa3b, v6
	v_rndne_f32_e32 v9, v7
	s_mov_b32 s18, 0x3fb8aa3b
	v_sub_f32_e32 v10, v7, v9
	v_fma_f32 v7, v6, s18, -v7
	v_fmac_f32_e32 v7, 0x32a5705f, v6
	v_add_f32_e32 v7, v10, v7
	v_cvt_i32_f32_e32 v9, v9
	v_exp_f32_e32 v7, v7
	s_mov_b32 s18, 0xc2ce8ed0
	v_cmp_ngt_f32_e32 vcc, s18, v6
	s_mov_b32 s18, 0x42b17218
	v_ldexp_f32 v7, v7, v9
	v_cndmask_b32_e32 v7, 0, v7, vcc
	v_cmp_nlt_f32_e32 vcc, s18, v6
	s_nop 1
	v_cndmask_b32_e32 v6, v188, v7, vcc
	v_add_f32_e32 v6, 1.0, v6
	v_rcp_f32_e32 v6, v6
	s_nop 0
	v_fma_f32 v6, v6, -2.0, 1.0
.Llst374_0:
	s_andn2_saveexec_b64 s[14:15], s[14:15]
	s_cbranch_execz .Llst369_0
	v_mul_f32_e32 v6, v5, v5
	v_fmamk_f32 v7, v6, 0xbbbac73d, v178
	v_fmaak_f32 v7, v6, v7, 0xbd5c1c4e
	v_fmaak_f32 v7, v6, v7, 0x3e088382
	v_fmaak_f32 v7, v6, v7, 0xbeaaaa99
	v_mul_f32_e64 v7, |v5|, v7
	v_fma_f32 v6, v6, v7, |v5|
.Llst369_0:
	s_or_b64 exec, exec, s[14:15]
	s_brev_b32 s14, -2
	v_bfi_b32 v5, s14, v6, v5
.Llst370_0:
	s_or_b64 exec, exec, s[12:13]
	v_bfe_u32 v6, v5, 16, 1
	s_movk_i32 s12, 0x210
	v_add3_u32 v5, v5, v6, s52
	v_mad_i32_i24 v4, v4, s12, v2
	ds_write_b16_d16_hi v4, v5
	v_add_u32_e32 v4, 0x100, v3
	v_mov_b32_e32 v3, v4
	v_ashrrev_i32_e32 v4, 8, v3
	s_waitcnt vmcnt(14)
	v_mov_b32_e32 v5, v89
	s_and_saveexec_b64 s[12:13], s[2:3]
	s_cbranch_execz .Llst370_1
	s_mov_b32 s14, 0x3f200000
	v_cmp_nlt_f32_e64 s[14:15], |v5|, s14
	s_and_saveexec_b64 s[18:19], s[14:15]
	s_xor_b64 s[14:15], exec, s[18:19]
	s_cbranch_execz .Llst374_1
	v_add_f32_e64 v6, |v5|, |v5|
	v_mul_f32_e32 v7, 0x3fb8aa3b, v6
	v_rndne_f32_e32 v9, v7
	s_mov_b32 s18, 0x3fb8aa3b
	v_sub_f32_e32 v10, v7, v9
	v_fma_f32 v7, v6, s18, -v7
	v_fmac_f32_e32 v7, 0x32a5705f, v6
	v_add_f32_e32 v7, v10, v7
	v_cvt_i32_f32_e32 v9, v9
	v_exp_f32_e32 v7, v7
	s_mov_b32 s18, 0xc2ce8ed0
	v_cmp_ngt_f32_e32 vcc, s18, v6
	s_mov_b32 s18, 0x42b17218
	v_ldexp_f32 v7, v7, v9
	v_cndmask_b32_e32 v7, 0, v7, vcc
	v_cmp_nlt_f32_e32 vcc, s18, v6
	s_nop 1
	v_cndmask_b32_e32 v6, v188, v7, vcc
	v_add_f32_e32 v6, 1.0, v6
	v_rcp_f32_e32 v6, v6
	s_nop 0
	v_fma_f32 v6, v6, -2.0, 1.0
.Llst374_1:
	s_andn2_saveexec_b64 s[14:15], s[14:15]
	s_cbranch_execz .Llst369_1
	v_mul_f32_e32 v6, v5, v5
	v_fmamk_f32 v7, v6, 0xbbbac73d, v178
	v_fmaak_f32 v7, v6, v7, 0xbd5c1c4e
	v_fmaak_f32 v7, v6, v7, 0x3e088382
	v_fmaak_f32 v7, v6, v7, 0xbeaaaa99
	v_mul_f32_e64 v7, |v5|, v7
	v_fma_f32 v6, v6, v7, |v5|
.Llst369_1:
	s_or_b64 exec, exec, s[14:15]
	s_brev_b32 s14, -2
	v_bfi_b32 v5, s14, v6, v5
.Llst370_1:
	s_or_b64 exec, exec, s[12:13]
	v_bfe_u32 v6, v5, 16, 1
	s_movk_i32 s12, 0x210
	v_add3_u32 v5, v5, v6, s52
	v_mad_i32_i24 v4, v4, s12, v2
	ds_write_b16_d16_hi v4, v5
	v_add_u32_e32 v4, 0x100, v3
	v_mov_b32_e32 v3, v4
	v_ashrrev_i32_e32 v4, 8, v3
	s_waitcnt vmcnt(13)
	v_mov_b32_e32 v5, v90
	s_and_saveexec_b64 s[12:13], s[2:3]
	s_cbranch_execz .Llst370_2
	s_mov_b32 s14, 0x3f200000
	v_cmp_nlt_f32_e64 s[14:15], |v5|, s14
	s_and_saveexec_b64 s[18:19], s[14:15]
	s_xor_b64 s[14:15], exec, s[18:19]
	s_cbranch_execz .Llst374_2
	v_add_f32_e64 v6, |v5|, |v5|
	v_mul_f32_e32 v7, 0x3fb8aa3b, v6
	v_rndne_f32_e32 v9, v7
	s_mov_b32 s18, 0x3fb8aa3b
	v_sub_f32_e32 v10, v7, v9
	v_fma_f32 v7, v6, s18, -v7
	v_fmac_f32_e32 v7, 0x32a5705f, v6
	v_add_f32_e32 v7, v10, v7
	v_cvt_i32_f32_e32 v9, v9
	v_exp_f32_e32 v7, v7
	s_mov_b32 s18, 0xc2ce8ed0
	v_cmp_ngt_f32_e32 vcc, s18, v6
	s_mov_b32 s18, 0x42b17218
	v_ldexp_f32 v7, v7, v9
	v_cndmask_b32_e32 v7, 0, v7, vcc
	v_cmp_nlt_f32_e32 vcc, s18, v6
	s_nop 1
	v_cndmask_b32_e32 v6, v188, v7, vcc
	v_add_f32_e32 v6, 1.0, v6
	v_rcp_f32_e32 v6, v6
	s_nop 0
	v_fma_f32 v6, v6, -2.0, 1.0
.Llst374_2:
	s_andn2_saveexec_b64 s[14:15], s[14:15]
	s_cbranch_execz .Llst369_2
	v_mul_f32_e32 v6, v5, v5
	v_fmamk_f32 v7, v6, 0xbbbac73d, v178
	v_fmaak_f32 v7, v6, v7, 0xbd5c1c4e
	v_fmaak_f32 v7, v6, v7, 0x3e088382
	v_fmaak_f32 v7, v6, v7, 0xbeaaaa99
	v_mul_f32_e64 v7, |v5|, v7
	v_fma_f32 v6, v6, v7, |v5|
.Llst369_2:
	s_or_b64 exec, exec, s[14:15]
	s_brev_b32 s14, -2
	v_bfi_b32 v5, s14, v6, v5
.Llst370_2:
	s_or_b64 exec, exec, s[12:13]
	v_bfe_u32 v6, v5, 16, 1
	s_movk_i32 s12, 0x210
	v_add3_u32 v5, v5, v6, s52
	v_mad_i32_i24 v4, v4, s12, v2
	ds_write_b16_d16_hi v4, v5
	v_add_u32_e32 v4, 0x100, v3
	v_mov_b32_e32 v3, v4
	v_ashrrev_i32_e32 v4, 8, v3
	s_waitcnt vmcnt(12)
	v_mov_b32_e32 v5, v91
	s_and_saveexec_b64 s[12:13], s[2:3]
	s_cbranch_execz .Llst370_3
	s_mov_b32 s14, 0x3f200000
	v_cmp_nlt_f32_e64 s[14:15], |v5|, s14
	s_and_saveexec_b64 s[18:19], s[14:15]
	s_xor_b64 s[14:15], exec, s[18:19]
	s_cbranch_execz .Llst374_3
	v_add_f32_e64 v6, |v5|, |v5|
	v_mul_f32_e32 v7, 0x3fb8aa3b, v6
	v_rndne_f32_e32 v9, v7
	s_mov_b32 s18, 0x3fb8aa3b
	v_sub_f32_e32 v10, v7, v9
	v_fma_f32 v7, v6, s18, -v7
	v_fmac_f32_e32 v7, 0x32a5705f, v6
	v_add_f32_e32 v7, v10, v7
	v_cvt_i32_f32_e32 v9, v9
	v_exp_f32_e32 v7, v7
	s_mov_b32 s18, 0xc2ce8ed0
	v_cmp_ngt_f32_e32 vcc, s18, v6
	s_mov_b32 s18, 0x42b17218
	v_ldexp_f32 v7, v7, v9
	v_cndmask_b32_e32 v7, 0, v7, vcc
	v_cmp_nlt_f32_e32 vcc, s18, v6
	s_nop 1
	v_cndmask_b32_e32 v6, v188, v7, vcc
	v_add_f32_e32 v6, 1.0, v6
	v_rcp_f32_e32 v6, v6
	s_nop 0
	v_fma_f32 v6, v6, -2.0, 1.0
.Llst374_3:
	s_andn2_saveexec_b64 s[14:15], s[14:15]
	s_cbranch_execz .Llst369_3
	v_mul_f32_e32 v6, v5, v5
	v_fmamk_f32 v7, v6, 0xbbbac73d, v178
	v_fmaak_f32 v7, v6, v7, 0xbd5c1c4e
	v_fmaak_f32 v7, v6, v7, 0x3e088382
	v_fmaak_f32 v7, v6, v7, 0xbeaaaa99
	v_mul_f32_e64 v7, |v5|, v7
	v_fma_f32 v6, v6, v7, |v5|
.Llst369_3:
	s_or_b64 exec, exec, s[14:15]
	s_brev_b32 s14, -2
	v_bfi_b32 v5, s14, v6, v5
.Llst370_3:
	s_or_b64 exec, exec, s[12:13]
	v_bfe_u32 v6, v5, 16, 1
	s_movk_i32 s12, 0x210
	v_add3_u32 v5, v5, v6, s52
	v_mad_i32_i24 v4, v4, s12, v2
	ds_write_b16_d16_hi v4, v5
	v_add_u32_e32 v4, 0x100, v3
	v_mov_b32_e32 v3, v4
	v_ashrrev_i32_e32 v4, 8, v3
	s_waitcnt vmcnt(11)
	v_mov_b32_e32 v5, v92
	s_and_saveexec_b64 s[12:13], s[2:3]
	s_cbranch_execz .Llst370_4
	s_mov_b32 s14, 0x3f200000
	v_cmp_nlt_f32_e64 s[14:15], |v5|, s14
	s_and_saveexec_b64 s[18:19], s[14:15]
	s_xor_b64 s[14:15], exec, s[18:19]
	s_cbranch_execz .Llst374_4
	v_add_f32_e64 v6, |v5|, |v5|
	v_mul_f32_e32 v7, 0x3fb8aa3b, v6
	v_rndne_f32_e32 v9, v7
	s_mov_b32 s18, 0x3fb8aa3b
	v_sub_f32_e32 v10, v7, v9
	v_fma_f32 v7, v6, s18, -v7
	v_fmac_f32_e32 v7, 0x32a5705f, v6
	v_add_f32_e32 v7, v10, v7
	v_cvt_i32_f32_e32 v9, v9
	v_exp_f32_e32 v7, v7
	s_mov_b32 s18, 0xc2ce8ed0
	v_cmp_ngt_f32_e32 vcc, s18, v6
	s_mov_b32 s18, 0x42b17218
	v_ldexp_f32 v7, v7, v9
	v_cndmask_b32_e32 v7, 0, v7, vcc
	v_cmp_nlt_f32_e32 vcc, s18, v6
	s_nop 1
	v_cndmask_b32_e32 v6, v188, v7, vcc
	v_add_f32_e32 v6, 1.0, v6
	v_rcp_f32_e32 v6, v6
	s_nop 0
	v_fma_f32 v6, v6, -2.0, 1.0
.Llst374_4:
	s_andn2_saveexec_b64 s[14:15], s[14:15]
	s_cbranch_execz .Llst369_4
	v_mul_f32_e32 v6, v5, v5
	v_fmamk_f32 v7, v6, 0xbbbac73d, v178
	v_fmaak_f32 v7, v6, v7, 0xbd5c1c4e
	v_fmaak_f32 v7, v6, v7, 0x3e088382
	v_fmaak_f32 v7, v6, v7, 0xbeaaaa99
	v_mul_f32_e64 v7, |v5|, v7
	v_fma_f32 v6, v6, v7, |v5|
.Llst369_4:
	s_or_b64 exec, exec, s[14:15]
	s_brev_b32 s14, -2
	v_bfi_b32 v5, s14, v6, v5
.Llst370_4:
	s_or_b64 exec, exec, s[12:13]
	v_bfe_u32 v6, v5, 16, 1
	s_movk_i32 s12, 0x210
	v_add3_u32 v5, v5, v6, s52
	v_mad_i32_i24 v4, v4, s12, v2
	ds_write_b16_d16_hi v4, v5
	v_add_u32_e32 v4, 0x100, v3
	v_mov_b32_e32 v3, v4
	v_ashrrev_i32_e32 v4, 8, v3
	s_waitcnt vmcnt(10)
	v_mov_b32_e32 v5, v93
	s_and_saveexec_b64 s[12:13], s[2:3]
	s_cbranch_execz .Llst370_5
	s_mov_b32 s14, 0x3f200000
	v_cmp_nlt_f32_e64 s[14:15], |v5|, s14
	s_and_saveexec_b64 s[18:19], s[14:15]
	s_xor_b64 s[14:15], exec, s[18:19]
	s_cbranch_execz .Llst374_5
	v_add_f32_e64 v6, |v5|, |v5|
	v_mul_f32_e32 v7, 0x3fb8aa3b, v6
	v_rndne_f32_e32 v9, v7
	s_mov_b32 s18, 0x3fb8aa3b
	v_sub_f32_e32 v10, v7, v9
	v_fma_f32 v7, v6, s18, -v7
	v_fmac_f32_e32 v7, 0x32a5705f, v6
	v_add_f32_e32 v7, v10, v7
	v_cvt_i32_f32_e32 v9, v9
	v_exp_f32_e32 v7, v7
	s_mov_b32 s18, 0xc2ce8ed0
	v_cmp_ngt_f32_e32 vcc, s18, v6
	s_mov_b32 s18, 0x42b17218
	v_ldexp_f32 v7, v7, v9
	v_cndmask_b32_e32 v7, 0, v7, vcc
	v_cmp_nlt_f32_e32 vcc, s18, v6
	s_nop 1
	v_cndmask_b32_e32 v6, v188, v7, vcc
	v_add_f32_e32 v6, 1.0, v6
	v_rcp_f32_e32 v6, v6
	s_nop 0
	v_fma_f32 v6, v6, -2.0, 1.0
.Llst374_5:
	s_andn2_saveexec_b64 s[14:15], s[14:15]
	s_cbranch_execz .Llst369_5
	v_mul_f32_e32 v6, v5, v5
	v_fmamk_f32 v7, v6, 0xbbbac73d, v178
	v_fmaak_f32 v7, v6, v7, 0xbd5c1c4e
	v_fmaak_f32 v7, v6, v7, 0x3e088382
	v_fmaak_f32 v7, v6, v7, 0xbeaaaa99
	v_mul_f32_e64 v7, |v5|, v7
	v_fma_f32 v6, v6, v7, |v5|
.Llst369_5:
	s_or_b64 exec, exec, s[14:15]
	s_brev_b32 s14, -2
	v_bfi_b32 v5, s14, v6, v5
.Llst370_5:
	s_or_b64 exec, exec, s[12:13]
	v_bfe_u32 v6, v5, 16, 1
	s_movk_i32 s12, 0x210
	v_add3_u32 v5, v5, v6, s52
	v_mad_i32_i24 v4, v4, s12, v2
	ds_write_b16_d16_hi v4, v5
	v_add_u32_e32 v4, 0x100, v3
	v_mov_b32_e32 v3, v4
	v_ashrrev_i32_e32 v4, 8, v3
	s_waitcnt vmcnt(9)
	v_mov_b32_e32 v5, v94
	s_and_saveexec_b64 s[12:13], s[2:3]
	s_cbranch_execz .Llst370_6
	s_mov_b32 s14, 0x3f200000
	v_cmp_nlt_f32_e64 s[14:15], |v5|, s14
	s_and_saveexec_b64 s[18:19], s[14:15]
	s_xor_b64 s[14:15], exec, s[18:19]
	s_cbranch_execz .Llst374_6
	v_add_f32_e64 v6, |v5|, |v5|
	v_mul_f32_e32 v7, 0x3fb8aa3b, v6
	v_rndne_f32_e32 v9, v7
	s_mov_b32 s18, 0x3fb8aa3b
	v_sub_f32_e32 v10, v7, v9
	v_fma_f32 v7, v6, s18, -v7
	v_fmac_f32_e32 v7, 0x32a5705f, v6
	v_add_f32_e32 v7, v10, v7
	v_cvt_i32_f32_e32 v9, v9
	v_exp_f32_e32 v7, v7
	s_mov_b32 s18, 0xc2ce8ed0
	v_cmp_ngt_f32_e32 vcc, s18, v6
	s_mov_b32 s18, 0x42b17218
	v_ldexp_f32 v7, v7, v9
	v_cndmask_b32_e32 v7, 0, v7, vcc
	v_cmp_nlt_f32_e32 vcc, s18, v6
	s_nop 1
	v_cndmask_b32_e32 v6, v188, v7, vcc
	v_add_f32_e32 v6, 1.0, v6
	v_rcp_f32_e32 v6, v6
	s_nop 0
	v_fma_f32 v6, v6, -2.0, 1.0
.Llst374_6:
	s_andn2_saveexec_b64 s[14:15], s[14:15]
	s_cbranch_execz .Llst369_6
	v_mul_f32_e32 v6, v5, v5
	v_fmamk_f32 v7, v6, 0xbbbac73d, v178
	v_fmaak_f32 v7, v6, v7, 0xbd5c1c4e
	v_fmaak_f32 v7, v6, v7, 0x3e088382
	v_fmaak_f32 v7, v6, v7, 0xbeaaaa99
	v_mul_f32_e64 v7, |v5|, v7
	v_fma_f32 v6, v6, v7, |v5|
.Llst369_6:
	s_or_b64 exec, exec, s[14:15]
	s_brev_b32 s14, -2
	v_bfi_b32 v5, s14, v6, v5
.Llst370_6:
	s_or_b64 exec, exec, s[12:13]
	v_bfe_u32 v6, v5, 16, 1
	s_movk_i32 s12, 0x210
	v_add3_u32 v5, v5, v6, s52
	v_mad_i32_i24 v4, v4, s12, v2
	ds_write_b16_d16_hi v4, v5
	v_add_u32_e32 v4, 0x100, v3
	v_mov_b32_e32 v3, v4
	v_ashrrev_i32_e32 v4, 8, v3
	s_waitcnt vmcnt(8)
	v_mov_b32_e32 v5, v95
	s_and_saveexec_b64 s[12:13], s[2:3]
	s_cbranch_execz .Llst370_7
	s_mov_b32 s14, 0x3f200000
	v_cmp_nlt_f32_e64 s[14:15], |v5|, s14
	s_and_saveexec_b64 s[18:19], s[14:15]
	s_xor_b64 s[14:15], exec, s[18:19]
	s_cbranch_execz .Llst374_7
	v_add_f32_e64 v6, |v5|, |v5|
	v_mul_f32_e32 v7, 0x3fb8aa3b, v6
	v_rndne_f32_e32 v9, v7
	s_mov_b32 s18, 0x3fb8aa3b
	v_sub_f32_e32 v10, v7, v9
	v_fma_f32 v7, v6, s18, -v7
	v_fmac_f32_e32 v7, 0x32a5705f, v6
	v_add_f32_e32 v7, v10, v7
	v_cvt_i32_f32_e32 v9, v9
	v_exp_f32_e32 v7, v7
	s_mov_b32 s18, 0xc2ce8ed0
	v_cmp_ngt_f32_e32 vcc, s18, v6
	s_mov_b32 s18, 0x42b17218
	v_ldexp_f32 v7, v7, v9
	v_cndmask_b32_e32 v7, 0, v7, vcc
	v_cmp_nlt_f32_e32 vcc, s18, v6
	s_nop 1
	v_cndmask_b32_e32 v6, v188, v7, vcc
	v_add_f32_e32 v6, 1.0, v6
	v_rcp_f32_e32 v6, v6
	s_nop 0
	v_fma_f32 v6, v6, -2.0, 1.0
.Llst374_7:
	s_andn2_saveexec_b64 s[14:15], s[14:15]
	s_cbranch_execz .Llst369_7
	v_mul_f32_e32 v6, v5, v5
	v_fmamk_f32 v7, v6, 0xbbbac73d, v178
	v_fmaak_f32 v7, v6, v7, 0xbd5c1c4e
	v_fmaak_f32 v7, v6, v7, 0x3e088382
	v_fmaak_f32 v7, v6, v7, 0xbeaaaa99
	v_mul_f32_e64 v7, |v5|, v7
	v_fma_f32 v6, v6, v7, |v5|
.Llst369_7:
	s_or_b64 exec, exec, s[14:15]
	s_brev_b32 s14, -2
	v_bfi_b32 v5, s14, v6, v5
.Llst370_7:
	s_or_b64 exec, exec, s[12:13]
	v_bfe_u32 v6, v5, 16, 1
	s_movk_i32 s12, 0x210
	v_add3_u32 v5, v5, v6, s52
	v_mad_i32_i24 v4, v4, s12, v2
	ds_write_b16_d16_hi v4, v5
	v_add_u32_e32 v4, 0x100, v3
	v_mov_b32_e32 v3, v4
	v_ashrrev_i32_e32 v4, 8, v3
	s_waitcnt vmcnt(7)
	v_mov_b32_e32 v5, v96
	s_and_saveexec_b64 s[12:13], s[2:3]
	s_cbranch_execz .Llst370_8
	s_mov_b32 s14, 0x3f200000
	v_cmp_nlt_f32_e64 s[14:15], |v5|, s14
	s_and_saveexec_b64 s[18:19], s[14:15]
	s_xor_b64 s[14:15], exec, s[18:19]
	s_cbranch_execz .Llst374_8
	v_add_f32_e64 v6, |v5|, |v5|
	v_mul_f32_e32 v7, 0x3fb8aa3b, v6
	v_rndne_f32_e32 v9, v7
	s_mov_b32 s18, 0x3fb8aa3b
	v_sub_f32_e32 v10, v7, v9
	v_fma_f32 v7, v6, s18, -v7
	v_fmac_f32_e32 v7, 0x32a5705f, v6
	v_add_f32_e32 v7, v10, v7
	v_cvt_i32_f32_e32 v9, v9
	v_exp_f32_e32 v7, v7
	s_mov_b32 s18, 0xc2ce8ed0
	v_cmp_ngt_f32_e32 vcc, s18, v6
	s_mov_b32 s18, 0x42b17218
	v_ldexp_f32 v7, v7, v9
	v_cndmask_b32_e32 v7, 0, v7, vcc
	v_cmp_nlt_f32_e32 vcc, s18, v6
	s_nop 1
	v_cndmask_b32_e32 v6, v188, v7, vcc
	v_add_f32_e32 v6, 1.0, v6
	v_rcp_f32_e32 v6, v6
	s_nop 0
	v_fma_f32 v6, v6, -2.0, 1.0
.Llst374_8:
	s_andn2_saveexec_b64 s[14:15], s[14:15]
	s_cbranch_execz .Llst369_8
	v_mul_f32_e32 v6, v5, v5
	v_fmamk_f32 v7, v6, 0xbbbac73d, v178
	v_fmaak_f32 v7, v6, v7, 0xbd5c1c4e
	v_fmaak_f32 v7, v6, v7, 0x3e088382
	v_fmaak_f32 v7, v6, v7, 0xbeaaaa99
	v_mul_f32_e64 v7, |v5|, v7
	v_fma_f32 v6, v6, v7, |v5|
.Llst369_8:
	s_or_b64 exec, exec, s[14:15]
	s_brev_b32 s14, -2
	v_bfi_b32 v5, s14, v6, v5
.Llst370_8:
	s_or_b64 exec, exec, s[12:13]
	v_bfe_u32 v6, v5, 16, 1
	s_movk_i32 s12, 0x210
	v_add3_u32 v5, v5, v6, s52
	v_mad_i32_i24 v4, v4, s12, v2
	ds_write_b16_d16_hi v4, v5
	v_add_u32_e32 v4, 0x100, v3
	v_mov_b32_e32 v3, v4
	v_ashrrev_i32_e32 v4, 8, v3
	s_waitcnt vmcnt(6)
	v_mov_b32_e32 v5, v97
	s_and_saveexec_b64 s[12:13], s[2:3]
	s_cbranch_execz .Llst370_9
	s_mov_b32 s14, 0x3f200000
	v_cmp_nlt_f32_e64 s[14:15], |v5|, s14
	s_and_saveexec_b64 s[18:19], s[14:15]
	s_xor_b64 s[14:15], exec, s[18:19]
	s_cbranch_execz .Llst374_9
	v_add_f32_e64 v6, |v5|, |v5|
	v_mul_f32_e32 v7, 0x3fb8aa3b, v6
	v_rndne_f32_e32 v9, v7
	s_mov_b32 s18, 0x3fb8aa3b
	v_sub_f32_e32 v10, v7, v9
	v_fma_f32 v7, v6, s18, -v7
	v_fmac_f32_e32 v7, 0x32a5705f, v6
	v_add_f32_e32 v7, v10, v7
	v_cvt_i32_f32_e32 v9, v9
	v_exp_f32_e32 v7, v7
	s_mov_b32 s18, 0xc2ce8ed0
	v_cmp_ngt_f32_e32 vcc, s18, v6
	s_mov_b32 s18, 0x42b17218
	v_ldexp_f32 v7, v7, v9
	v_cndmask_b32_e32 v7, 0, v7, vcc
	v_cmp_nlt_f32_e32 vcc, s18, v6
	s_nop 1
	v_cndmask_b32_e32 v6, v188, v7, vcc
	v_add_f32_e32 v6, 1.0, v6
	v_rcp_f32_e32 v6, v6
	s_nop 0
	v_fma_f32 v6, v6, -2.0, 1.0
.Llst374_9:
	s_andn2_saveexec_b64 s[14:15], s[14:15]
	s_cbranch_execz .Llst369_9
	v_mul_f32_e32 v6, v5, v5
	v_fmamk_f32 v7, v6, 0xbbbac73d, v178
	v_fmaak_f32 v7, v6, v7, 0xbd5c1c4e
	v_fmaak_f32 v7, v6, v7, 0x3e088382
	v_fmaak_f32 v7, v6, v7, 0xbeaaaa99
	v_mul_f32_e64 v7, |v5|, v7
	v_fma_f32 v6, v6, v7, |v5|
.Llst369_9:
	s_or_b64 exec, exec, s[14:15]
	s_brev_b32 s14, -2
	v_bfi_b32 v5, s14, v6, v5
.Llst370_9:
	s_or_b64 exec, exec, s[12:13]
	v_bfe_u32 v6, v5, 16, 1
	s_movk_i32 s12, 0x210
	v_add3_u32 v5, v5, v6, s52
	v_mad_i32_i24 v4, v4, s12, v2
	ds_write_b16_d16_hi v4, v5
	v_add_u32_e32 v4, 0x100, v3
	v_mov_b32_e32 v3, v4
	v_ashrrev_i32_e32 v4, 8, v3
	s_waitcnt vmcnt(5)
	v_mov_b32_e32 v5, v98
	s_and_saveexec_b64 s[12:13], s[2:3]
	s_cbranch_execz .Llst370_10
	s_mov_b32 s14, 0x3f200000
	v_cmp_nlt_f32_e64 s[14:15], |v5|, s14
	s_and_saveexec_b64 s[18:19], s[14:15]
	s_xor_b64 s[14:15], exec, s[18:19]
	s_cbranch_execz .Llst374_10
	v_add_f32_e64 v6, |v5|, |v5|
	v_mul_f32_e32 v7, 0x3fb8aa3b, v6
	v_rndne_f32_e32 v9, v7
	s_mov_b32 s18, 0x3fb8aa3b
	v_sub_f32_e32 v10, v7, v9
	v_fma_f32 v7, v6, s18, -v7
	v_fmac_f32_e32 v7, 0x32a5705f, v6
	v_add_f32_e32 v7, v10, v7
	v_cvt_i32_f32_e32 v9, v9
	v_exp_f32_e32 v7, v7
	s_mov_b32 s18, 0xc2ce8ed0
	v_cmp_ngt_f32_e32 vcc, s18, v6
	s_mov_b32 s18, 0x42b17218
	v_ldexp_f32 v7, v7, v9
	v_cndmask_b32_e32 v7, 0, v7, vcc
	v_cmp_nlt_f32_e32 vcc, s18, v6
	s_nop 1
	v_cndmask_b32_e32 v6, v188, v7, vcc
	v_add_f32_e32 v6, 1.0, v6
	v_rcp_f32_e32 v6, v6
	s_nop 0
	v_fma_f32 v6, v6, -2.0, 1.0
.Llst374_10:
	s_andn2_saveexec_b64 s[14:15], s[14:15]
	s_cbranch_execz .Llst369_10
	v_mul_f32_e32 v6, v5, v5
	v_fmamk_f32 v7, v6, 0xbbbac73d, v178
	v_fmaak_f32 v7, v6, v7, 0xbd5c1c4e
	v_fmaak_f32 v7, v6, v7, 0x3e088382
	v_fmaak_f32 v7, v6, v7, 0xbeaaaa99
	v_mul_f32_e64 v7, |v5|, v7
	v_fma_f32 v6, v6, v7, |v5|
.Llst369_10:
	s_or_b64 exec, exec, s[14:15]
	s_brev_b32 s14, -2
	v_bfi_b32 v5, s14, v6, v5
.Llst370_10:
	s_or_b64 exec, exec, s[12:13]
	v_bfe_u32 v6, v5, 16, 1
	s_movk_i32 s12, 0x210
	v_add3_u32 v5, v5, v6, s52
	v_mad_i32_i24 v4, v4, s12, v2
	ds_write_b16_d16_hi v4, v5
	v_add_u32_e32 v4, 0x100, v3
	v_mov_b32_e32 v3, v4
	v_ashrrev_i32_e32 v4, 8, v3
	s_waitcnt vmcnt(4)
	v_mov_b32_e32 v5, v99
	s_and_saveexec_b64 s[12:13], s[2:3]
	s_cbranch_execz .Llst370_11
	s_mov_b32 s14, 0x3f200000
	v_cmp_nlt_f32_e64 s[14:15], |v5|, s14
	s_and_saveexec_b64 s[18:19], s[14:15]
	s_xor_b64 s[14:15], exec, s[18:19]
	s_cbranch_execz .Llst374_11
	v_add_f32_e64 v6, |v5|, |v5|
	v_mul_f32_e32 v7, 0x3fb8aa3b, v6
	v_rndne_f32_e32 v9, v7
	s_mov_b32 s18, 0x3fb8aa3b
	v_sub_f32_e32 v10, v7, v9
	v_fma_f32 v7, v6, s18, -v7
	v_fmac_f32_e32 v7, 0x32a5705f, v6
	v_add_f32_e32 v7, v10, v7
	v_cvt_i32_f32_e32 v9, v9
	v_exp_f32_e32 v7, v7
	s_mov_b32 s18, 0xc2ce8ed0
	v_cmp_ngt_f32_e32 vcc, s18, v6
	s_mov_b32 s18, 0x42b17218
	v_ldexp_f32 v7, v7, v9
	v_cndmask_b32_e32 v7, 0, v7, vcc
	v_cmp_nlt_f32_e32 vcc, s18, v6
	s_nop 1
	v_cndmask_b32_e32 v6, v188, v7, vcc
	v_add_f32_e32 v6, 1.0, v6
	v_rcp_f32_e32 v6, v6
	s_nop 0
	v_fma_f32 v6, v6, -2.0, 1.0
.Llst374_11:
	s_andn2_saveexec_b64 s[14:15], s[14:15]
	s_cbranch_execz .Llst369_11
	v_mul_f32_e32 v6, v5, v5
	v_fmamk_f32 v7, v6, 0xbbbac73d, v178
	v_fmaak_f32 v7, v6, v7, 0xbd5c1c4e
	v_fmaak_f32 v7, v6, v7, 0x3e088382
	v_fmaak_f32 v7, v6, v7, 0xbeaaaa99
	v_mul_f32_e64 v7, |v5|, v7
	v_fma_f32 v6, v6, v7, |v5|
.Llst369_11:
	s_or_b64 exec, exec, s[14:15]
	s_brev_b32 s14, -2
	v_bfi_b32 v5, s14, v6, v5
.Llst370_11:
	s_or_b64 exec, exec, s[12:13]
	v_bfe_u32 v6, v5, 16, 1
	s_movk_i32 s12, 0x210
	v_add3_u32 v5, v5, v6, s52
	v_mad_i32_i24 v4, v4, s12, v2
	ds_write_b16_d16_hi v4, v5
	v_add_u32_e32 v4, 0x100, v3
	v_mov_b32_e32 v3, v4
	v_ashrrev_i32_e32 v4, 8, v3
	s_waitcnt vmcnt(3)
	v_mov_b32_e32 v5, v100
	s_and_saveexec_b64 s[12:13], s[2:3]
	s_cbranch_execz .Llst370_12
	s_mov_b32 s14, 0x3f200000
	v_cmp_nlt_f32_e64 s[14:15], |v5|, s14
	s_and_saveexec_b64 s[18:19], s[14:15]
	s_xor_b64 s[14:15], exec, s[18:19]
	s_cbranch_execz .Llst374_12
	v_add_f32_e64 v6, |v5|, |v5|
	v_mul_f32_e32 v7, 0x3fb8aa3b, v6
	v_rndne_f32_e32 v9, v7
	s_mov_b32 s18, 0x3fb8aa3b
	v_sub_f32_e32 v10, v7, v9
	v_fma_f32 v7, v6, s18, -v7
	v_fmac_f32_e32 v7, 0x32a5705f, v6
	v_add_f32_e32 v7, v10, v7
	v_cvt_i32_f32_e32 v9, v9
	v_exp_f32_e32 v7, v7
	s_mov_b32 s18, 0xc2ce8ed0
	v_cmp_ngt_f32_e32 vcc, s18, v6
	s_mov_b32 s18, 0x42b17218
	v_ldexp_f32 v7, v7, v9
	v_cndmask_b32_e32 v7, 0, v7, vcc
	v_cmp_nlt_f32_e32 vcc, s18, v6
	s_nop 1
	v_cndmask_b32_e32 v6, v188, v7, vcc
	v_add_f32_e32 v6, 1.0, v6
	v_rcp_f32_e32 v6, v6
	s_nop 0
	v_fma_f32 v6, v6, -2.0, 1.0
.Llst374_12:
	s_andn2_saveexec_b64 s[14:15], s[14:15]
	s_cbranch_execz .Llst369_12
	v_mul_f32_e32 v6, v5, v5
	v_fmamk_f32 v7, v6, 0xbbbac73d, v178
	v_fmaak_f32 v7, v6, v7, 0xbd5c1c4e
	v_fmaak_f32 v7, v6, v7, 0x3e088382
	v_fmaak_f32 v7, v6, v7, 0xbeaaaa99
	v_mul_f32_e64 v7, |v5|, v7
	v_fma_f32 v6, v6, v7, |v5|
.Llst369_12:
	s_or_b64 exec, exec, s[14:15]
	s_brev_b32 s14, -2
	v_bfi_b32 v5, s14, v6, v5
.Llst370_12:
	s_or_b64 exec, exec, s[12:13]
	v_bfe_u32 v6, v5, 16, 1
	s_movk_i32 s12, 0x210
	v_add3_u32 v5, v5, v6, s52
	v_mad_i32_i24 v4, v4, s12, v2
	ds_write_b16_d16_hi v4, v5
	v_add_u32_e32 v4, 0x100, v3
	v_mov_b32_e32 v3, v4
	v_ashrrev_i32_e32 v4, 8, v3
	s_waitcnt vmcnt(2)
	v_mov_b32_e32 v5, v101
	s_and_saveexec_b64 s[12:13], s[2:3]
	s_cbranch_execz .Llst370_13
	s_mov_b32 s14, 0x3f200000
	v_cmp_nlt_f32_e64 s[14:15], |v5|, s14
	s_and_saveexec_b64 s[18:19], s[14:15]
	s_xor_b64 s[14:15], exec, s[18:19]
	s_cbranch_execz .Llst374_13
	v_add_f32_e64 v6, |v5|, |v5|
	v_mul_f32_e32 v7, 0x3fb8aa3b, v6
	v_rndne_f32_e32 v9, v7
	s_mov_b32 s18, 0x3fb8aa3b
	v_sub_f32_e32 v10, v7, v9
	v_fma_f32 v7, v6, s18, -v7
	v_fmac_f32_e32 v7, 0x32a5705f, v6
	v_add_f32_e32 v7, v10, v7
	v_cvt_i32_f32_e32 v9, v9
	v_exp_f32_e32 v7, v7
	s_mov_b32 s18, 0xc2ce8ed0
	v_cmp_ngt_f32_e32 vcc, s18, v6
	s_mov_b32 s18, 0x42b17218
	v_ldexp_f32 v7, v7, v9
	v_cndmask_b32_e32 v7, 0, v7, vcc
	v_cmp_nlt_f32_e32 vcc, s18, v6
	s_nop 1
	v_cndmask_b32_e32 v6, v188, v7, vcc
	v_add_f32_e32 v6, 1.0, v6
	v_rcp_f32_e32 v6, v6
	s_nop 0
	v_fma_f32 v6, v6, -2.0, 1.0
.Llst374_13:
	s_andn2_saveexec_b64 s[14:15], s[14:15]
	s_cbranch_execz .Llst369_13
	v_mul_f32_e32 v6, v5, v5
	v_fmamk_f32 v7, v6, 0xbbbac73d, v178
	v_fmaak_f32 v7, v6, v7, 0xbd5c1c4e
	v_fmaak_f32 v7, v6, v7, 0x3e088382
	v_fmaak_f32 v7, v6, v7, 0xbeaaaa99
	v_mul_f32_e64 v7, |v5|, v7
	v_fma_f32 v6, v6, v7, |v5|
.Llst369_13:
	s_or_b64 exec, exec, s[14:15]
	s_brev_b32 s14, -2
	v_bfi_b32 v5, s14, v6, v5
.Llst370_13:
	s_or_b64 exec, exec, s[12:13]
	v_bfe_u32 v6, v5, 16, 1
	s_movk_i32 s12, 0x210
	v_add3_u32 v5, v5, v6, s52
	v_mad_i32_i24 v4, v4, s12, v2
	ds_write_b16_d16_hi v4, v5
	v_add_u32_e32 v4, 0x100, v3
	v_mov_b32_e32 v3, v4
	v_ashrrev_i32_e32 v4, 8, v3
	s_waitcnt vmcnt(1)
	v_mov_b32_e32 v5, v102
	s_and_saveexec_b64 s[12:13], s[2:3]
	s_cbranch_execz .Llst370_14
	s_mov_b32 s14, 0x3f200000
	v_cmp_nlt_f32_e64 s[14:15], |v5|, s14
	s_and_saveexec_b64 s[18:19], s[14:15]
	s_xor_b64 s[14:15], exec, s[18:19]
	s_cbranch_execz .Llst374_14
	v_add_f32_e64 v6, |v5|, |v5|
	v_mul_f32_e32 v7, 0x3fb8aa3b, v6
	v_rndne_f32_e32 v9, v7
	s_mov_b32 s18, 0x3fb8aa3b
	v_sub_f32_e32 v10, v7, v9
	v_fma_f32 v7, v6, s18, -v7
	v_fmac_f32_e32 v7, 0x32a5705f, v6
	v_add_f32_e32 v7, v10, v7
	v_cvt_i32_f32_e32 v9, v9
	v_exp_f32_e32 v7, v7
	s_mov_b32 s18, 0xc2ce8ed0
	v_cmp_ngt_f32_e32 vcc, s18, v6
	s_mov_b32 s18, 0x42b17218
	v_ldexp_f32 v7, v7, v9
	v_cndmask_b32_e32 v7, 0, v7, vcc
	v_cmp_nlt_f32_e32 vcc, s18, v6
	s_nop 1
	v_cndmask_b32_e32 v6, v188, v7, vcc
	v_add_f32_e32 v6, 1.0, v6
	v_rcp_f32_e32 v6, v6
	s_nop 0
	v_fma_f32 v6, v6, -2.0, 1.0
.Llst374_14:
	s_andn2_saveexec_b64 s[14:15], s[14:15]
	s_cbranch_execz .Llst369_14
	v_mul_f32_e32 v6, v5, v5
	v_fmamk_f32 v7, v6, 0xbbbac73d, v178
	v_fmaak_f32 v7, v6, v7, 0xbd5c1c4e
	v_fmaak_f32 v7, v6, v7, 0x3e088382
	v_fmaak_f32 v7, v6, v7, 0xbeaaaa99
	v_mul_f32_e64 v7, |v5|, v7
	v_fma_f32 v6, v6, v7, |v5|
.Llst369_14:
	s_or_b64 exec, exec, s[14:15]
	s_brev_b32 s14, -2
	v_bfi_b32 v5, s14, v6, v5
.Llst370_14:
	s_or_b64 exec, exec, s[12:13]
	v_bfe_u32 v6, v5, 16, 1
	s_movk_i32 s12, 0x210
	v_add3_u32 v5, v5, v6, s52
	v_mad_i32_i24 v4, v4, s12, v2
	ds_write_b16_d16_hi v4, v5
	v_add_u32_e32 v4, 0x100, v3
	v_mov_b32_e32 v3, v4
	v_ashrrev_i32_e32 v4, 8, v3
	s_waitcnt vmcnt(0)
	v_mov_b32_e32 v5, v103
	s_and_saveexec_b64 s[12:13], s[2:3]
	s_cbranch_execz .Llst370_15
	s_mov_b32 s14, 0x3f200000
	v_cmp_nlt_f32_e64 s[14:15], |v5|, s14
	s_and_saveexec_b64 s[18:19], s[14:15]
	s_xor_b64 s[14:15], exec, s[18:19]
	s_cbranch_execz .Llst374_15
	v_add_f32_e64 v6, |v5|, |v5|
	v_mul_f32_e32 v7, 0x3fb8aa3b, v6
	v_rndne_f32_e32 v9, v7
	s_mov_b32 s18, 0x3fb8aa3b
	v_sub_f32_e32 v10, v7, v9
	v_fma_f32 v7, v6, s18, -v7
	v_fmac_f32_e32 v7, 0x32a5705f, v6
	v_add_f32_e32 v7, v10, v7
	v_cvt_i32_f32_e32 v9, v9
	v_exp_f32_e32 v7, v7
	s_mov_b32 s18, 0xc2ce8ed0
	v_cmp_ngt_f32_e32 vcc, s18, v6
	s_mov_b32 s18, 0x42b17218
	v_ldexp_f32 v7, v7, v9
	v_cndmask_b32_e32 v7, 0, v7, vcc
	v_cmp_nlt_f32_e32 vcc, s18, v6
	s_nop 1
	v_cndmask_b32_e32 v6, v188, v7, vcc
	v_add_f32_e32 v6, 1.0, v6
	v_rcp_f32_e32 v6, v6
	s_nop 0
	v_fma_f32 v6, v6, -2.0, 1.0
.Llst374_15:
	s_andn2_saveexec_b64 s[14:15], s[14:15]
	s_cbranch_execz .Llst369_15
	v_mul_f32_e32 v6, v5, v5
	v_fmamk_f32 v7, v6, 0xbbbac73d, v178
	v_fmaak_f32 v7, v6, v7, 0xbd5c1c4e
	v_fmaak_f32 v7, v6, v7, 0x3e088382
	v_fmaak_f32 v7, v6, v7, 0xbeaaaa99
	v_mul_f32_e64 v7, |v5|, v7
	v_fma_f32 v6, v6, v7, |v5|
.Llst369_15:
	s_or_b64 exec, exec, s[14:15]
	s_brev_b32 s14, -2
	v_bfi_b32 v5, s14, v6, v5
.Llst370_15:
	s_or_b64 exec, exec, s[12:13]
	v_bfe_u32 v6, v5, 16, 1
	s_movk_i32 s12, 0x210
	v_add3_u32 v5, v5, v6, s52
	v_mad_i32_i24 v4, v4, s12, v2
	ds_write_b16_d16_hi v4, v5
	v_add_u32_e32 v4, 0x100, v3
	v_mov_b32_e32 v3, v4

.LBB0_517:
	v_mov_b32_e32 v88, v1
	v_lshlrev_b32_e32 v89, 2, v88
	v_ashrrev_i32_e32 v90, 6, v88
	v_lshlrev_b32_e32 v94, 2, v90
	v_add_u32_e32 v90, 0x11000, v94
	ds_read_b32 v90, v90
	v_and_b32_e32 v95, 0xfc, v89
	v_lshlrev_b32_e32 v96, 2, v95
	v_mov_b32_e32 v97, 0
	v_mad_u32_u24 v94, v95, s22, v94
	v_add_u32_e32 v98, 0x100, v1
	v_lshlrev_b32_e32 v99, 2, v98
	v_ashrrev_i32_e32 v100, 6, v98
	v_lshlrev_b32_e32 v104, 2, v100
	v_add_u32_e32 v100, 0x11000, v104
	ds_read_b32 v100, v100
	v_and_b32_e32 v105, 0xfc, v99
	v_lshlrev_b32_e32 v106, 2, v105
	v_mov_b32_e32 v107, 0
	v_mad_u32_u24 v104, v105, s22, v104
	v_add_u32_e32 v108, 0x200, v1
	v_lshlrev_b32_e32 v109, 2, v108
	v_ashrrev_i32_e32 v110, 6, v108
	v_lshlrev_b32_e32 v114, 2, v110
	v_add_u32_e32 v110, 0x11000, v114
	ds_read_b32 v110, v110
	v_and_b32_e32 v115, 0xfc, v109
	v_lshlrev_b32_e32 v116, 2, v115
	v_mov_b32_e32 v117, 0
	v_mad_u32_u24 v114, v115, s22, v114
	v_add_u32_e32 v118, 0x300, v1
	v_lshlrev_b32_e32 v119, 2, v118
	v_ashrrev_i32_e32 v120, 6, v118
	v_lshlrev_b32_e32 v124, 2, v120
	v_add_u32_e32 v120, 0x11000, v124
	ds_read_b32 v120, v120
	v_and_b32_e32 v125, 0xfc, v119
	v_lshlrev_b32_e32 v126, 2, v125
	v_mov_b32_e32 v127, 0
	v_mad_u32_u24 v124, v125, s22, v124
	v_add_u32_e32 v128, 0x400, v1
	v_lshlrev_b32_e32 v129, 2, v128
	v_ashrrev_i32_e32 v130, 6, v128
	v_lshlrev_b32_e32 v134, 2, v130
	v_add_u32_e32 v130, 0x11000, v134
	ds_read_b32 v130, v130
	v_and_b32_e32 v135, 0xfc, v129
	v_lshlrev_b32_e32 v136, 2, v135
	v_mov_b32_e32 v137, 0
	v_mad_u32_u24 v134, v135, s22, v134
	v_add_u32_e32 v152, 0x500, v1
	v_lshlrev_b32_e32 v153, 2, v152
	v_ashrrev_i32_e32 v154, 6, v152
	v_lshlrev_b32_e32 v158, 2, v154
	v_add_u32_e32 v154, 0x11000, v158
	ds_read_b32 v154, v154
	v_and_b32_e32 v159, 0xfc, v153
	v_lshlrev_b32_e32 v160, 2, v159
	v_mov_b32_e32 v161, 0
	v_mad_u32_u24 v158, v159, s22, v158
	v_add_u32_e32 v162, 0x600, v1
	v_lshlrev_b32_e32 v163, 2, v162
	v_ashrrev_i32_e32 v164, 6, v162
	v_lshlrev_b32_e32 v168, 2, v164
	v_add_u32_e32 v164, 0x11000, v168
	ds_read_b32 v164, v164
	v_and_b32_e32 v169, 0xfc, v163
	v_lshlrev_b32_e32 v170, 2, v169
	v_mov_b32_e32 v171, 0
	v_mad_u32_u24 v168, v169, s22, v168
	v_add_u32_e32 v204, 0x700, v1
	v_lshlrev_b32_e32 v205, 2, v204
	v_ashrrev_i32_e32 v206, 6, v204
	v_lshlrev_b32_e32 v210, 2, v206
	v_add_u32_e32 v206, 0x11000, v210
	ds_read_b32 v206, v206
	v_and_b32_e32 v211, 0xfc, v205
	v_lshlrev_b32_e32 v212, 2, v211
	v_mov_b32_e32 v213, 0
	v_mad_u32_u24 v210, v211, s22, v210
	s_waitcnt lgkmcnt(7)
	v_ashrrev_i32_e32 v91, 31, v90
	v_lshlrev_b64 v[90:91], 10, v[90:91]
	v_lshl_add_u64 v[90:91], s[16:17], 0, v[90:91]
	v_lshl_add_u64 v[90:91], v[90:91], 0, v[96:97]
	global_load_dwordx4 v[90:93], v[90:91], off
	s_waitcnt lgkmcnt(6)
	v_ashrrev_i32_e32 v101, 31, v100
	v_lshlrev_b64 v[100:101], 10, v[100:101]
	v_lshl_add_u64 v[100:101], s[16:17], 0, v[100:101]
	v_lshl_add_u64 v[100:101], v[100:101], 0, v[106:107]
	global_load_dwordx4 v[100:103], v[100:101], off
	s_waitcnt lgkmcnt(5)
	v_ashrrev_i32_e32 v111, 31, v110
	v_lshlrev_b64 v[110:111], 10, v[110:111]
	v_lshl_add_u64 v[110:111], s[16:17], 0, v[110:111]
	v_lshl_add_u64 v[110:111], v[110:111], 0, v[116:117]
	global_load_dwordx4 v[110:113], v[110:111], off
	s_waitcnt lgkmcnt(4)
	v_ashrrev_i32_e32 v121, 31, v120
	v_lshlrev_b64 v[120:121], 10, v[120:121]
	v_lshl_add_u64 v[120:121], s[16:17], 0, v[120:121]
	v_lshl_add_u64 v[120:121], v[120:121], 0, v[126:127]
	global_load_dwordx4 v[120:123], v[120:121], off
	s_waitcnt lgkmcnt(3)
	v_ashrrev_i32_e32 v131, 31, v130
	v_lshlrev_b64 v[130:131], 10, v[130:131]
	v_lshl_add_u64 v[130:131], s[16:17], 0, v[130:131]
	v_lshl_add_u64 v[130:131], v[130:131], 0, v[136:137]
	global_load_dwordx4 v[130:133], v[130:131], off
	s_waitcnt lgkmcnt(2)
	v_ashrrev_i32_e32 v155, 31, v154
	v_lshlrev_b64 v[154:155], 10, v[154:155]
	v_lshl_add_u64 v[154:155], s[16:17], 0, v[154:155]
	v_lshl_add_u64 v[154:155], v[154:155], 0, v[160:161]
	global_load_dwordx4 v[154:157], v[154:155], off
	s_waitcnt lgkmcnt(1)
	v_ashrrev_i32_e32 v165, 31, v164
	v_lshlrev_b64 v[164:165], 10, v[164:165]
	v_lshl_add_u64 v[164:165], s[16:17], 0, v[164:165]
	v_lshl_add_u64 v[164:165], v[164:165], 0, v[170:171]
	global_load_dwordx4 v[164:167], v[164:165], off
	s_waitcnt lgkmcnt(0)
	v_ashrrev_i32_e32 v207, 31, v206
	v_lshlrev_b64 v[206:207], 10, v[206:207]
	v_lshl_add_u64 v[206:207], s[16:17], 0, v[206:207]
	v_lshl_add_u64 v[206:207], v[206:207], 0, v[212:213]
	global_load_dwordx4 v[206:209], v[206:207], off
	s_waitcnt vmcnt(7)
	ds_write2_b32 v94, v90, v91 offset1:68
	ds_write2_b32 v94, v92, v93 offset0:136 offset1:204
	s_waitcnt vmcnt(6)
	ds_write2_b32 v104, v100, v101 offset1:68
	ds_write2_b32 v104, v102, v103 offset0:136 offset1:204
	s_waitcnt vmcnt(5)
	ds_write2_b32 v114, v110, v111 offset1:68
	ds_write2_b32 v114, v112, v113 offset0:136 offset1:204
	s_waitcnt vmcnt(4)
	ds_write2_b32 v124, v120, v121 offset1:68
	ds_write2_b32 v124, v122, v123 offset0:136 offset1:204
	s_waitcnt vmcnt(3)
	ds_write2_b32 v134, v130, v131 offset1:68
	ds_write2_b32 v134, v132, v133 offset0:136 offset1:204
	s_waitcnt vmcnt(2)
	ds_write2_b32 v158, v154, v155 offset1:68
	ds_write2_b32 v158, v156, v157 offset0:136 offset1:204
	s_waitcnt vmcnt(1)
	ds_write2_b32 v168, v164, v165 offset1:68
	ds_write2_b32 v168, v166, v167 offset0:136 offset1:204
	s_waitcnt vmcnt(0)
	ds_write2_b32 v210, v206, v207 offset1:68
	ds_write2_b32 v210, v208, v209 offset0:136 offset1:204
	v_add_u32_e32 v88, 0x800, v1
	v_lshlrev_b32_e32 v89, 2, v88
	v_ashrrev_i32_e32 v90, 6, v88
	v_lshlrev_b32_e32 v94, 2, v90
	v_add_u32_e32 v90, 0x11000, v94
	ds_read_b32 v90, v90
	v_and_b32_e32 v95, 0xfc, v89
	v_lshlrev_b32_e32 v96, 2, v95
	v_mov_b32_e32 v97, 0
	v_mad_u32_u24 v94, v95, s22, v94
	v_add_u32_e32 v98, 0x900, v1
	v_lshlrev_b32_e32 v99, 2, v98
	v_ashrrev_i32_e32 v100, 6, v98
	v_lshlrev_b32_e32 v104, 2, v100
	v_add_u32_e32 v100, 0x11000, v104
	ds_read_b32 v100, v100
	v_and_b32_e32 v105, 0xfc, v99
	v_lshlrev_b32_e32 v106, 2, v105
	v_mov_b32_e32 v107, 0
	v_mad_u32_u24 v104, v105, s22, v104
	v_add_u32_e32 v108, 0xa00, v1
	v_lshlrev_b32_e32 v109, 2, v108
	v_ashrrev_i32_e32 v110, 6, v108
	v_lshlrev_b32_e32 v114, 2, v110
	v_add_u32_e32 v110, 0x11000, v114
	ds_read_b32 v110, v110
	v_and_b32_e32 v115, 0xfc, v109
	v_lshlrev_b32_e32 v116, 2, v115
	v_mov_b32_e32 v117, 0
	v_mad_u32_u24 v114, v115, s22, v114
	v_add_u32_e32 v118, 0xb00, v1
	v_lshlrev_b32_e32 v119, 2, v118
	v_ashrrev_i32_e32 v120, 6, v118
	v_lshlrev_b32_e32 v124, 2, v120
	v_add_u32_e32 v120, 0x11000, v124
	ds_read_b32 v120, v120
	v_and_b32_e32 v125, 0xfc, v119
	v_lshlrev_b32_e32 v126, 2, v125
	v_mov_b32_e32 v127, 0
	v_mad_u32_u24 v124, v125, s22, v124
	v_add_u32_e32 v128, 0xc00, v1
	v_lshlrev_b32_e32 v129, 2, v128
	v_ashrrev_i32_e32 v130, 6, v128
	v_lshlrev_b32_e32 v134, 2, v130
	v_add_u32_e32 v130, 0x11000, v134
	ds_read_b32 v130, v130
	v_and_b32_e32 v135, 0xfc, v129
	v_lshlrev_b32_e32 v136, 2, v135
	v_mov_b32_e32 v137, 0
	v_mad_u32_u24 v134, v135, s22, v134
	v_add_u32_e32 v152, 0xd00, v1
	v_lshlrev_b32_e32 v153, 2, v152
	v_ashrrev_i32_e32 v154, 6, v152
	v_lshlrev_b32_e32 v158, 2, v154
	v_add_u32_e32 v154, 0x11000, v158
	ds_read_b32 v154, v154
	v_and_b32_e32 v159, 0xfc, v153
	v_lshlrev_b32_e32 v160, 2, v159
	v_mov_b32_e32 v161, 0
	v_mad_u32_u24 v158, v159, s22, v158
	v_add_u32_e32 v162, 0xe00, v1
	v_lshlrev_b32_e32 v163, 2, v162
	v_ashrrev_i32_e32 v164, 6, v162
	v_lshlrev_b32_e32 v168, 2, v164
	v_add_u32_e32 v164, 0x11000, v168
	ds_read_b32 v164, v164
	v_and_b32_e32 v169, 0xfc, v163
	v_lshlrev_b32_e32 v170, 2, v169
	v_mov_b32_e32 v171, 0
	v_mad_u32_u24 v168, v169, s22, v168
	v_add_u32_e32 v204, 0xf00, v1
	v_lshlrev_b32_e32 v205, 2, v204
	v_ashrrev_i32_e32 v206, 6, v204
	v_lshlrev_b32_e32 v210, 2, v206
	v_add_u32_e32 v206, 0x11000, v210
	ds_read_b32 v206, v206
	v_and_b32_e32 v211, 0xfc, v205
	v_lshlrev_b32_e32 v212, 2, v211
	v_mov_b32_e32 v213, 0
	v_mad_u32_u24 v210, v211, s22, v210
	s_waitcnt lgkmcnt(7)
	v_ashrrev_i32_e32 v91, 31, v90
	v_lshlrev_b64 v[90:91], 10, v[90:91]
	v_lshl_add_u64 v[90:91], s[16:17], 0, v[90:91]
	v_lshl_add_u64 v[90:91], v[90:91], 0, v[96:97]
	global_load_dwordx4 v[90:93], v[90:91], off
	s_waitcnt lgkmcnt(6)
	v_ashrrev_i32_e32 v101, 31, v100
	v_lshlrev_b64 v[100:101], 10, v[100:101]
	v_lshl_add_u64 v[100:101], s[16:17], 0, v[100:101]
	v_lshl_add_u64 v[100:101], v[100:101], 0, v[106:107]
	global_load_dwordx4 v[100:103], v[100:101], off
	s_waitcnt lgkmcnt(5)
	v_ashrrev_i32_e32 v111, 31, v110
	v_lshlrev_b64 v[110:111], 10, v[110:111]
	v_lshl_add_u64 v[110:111], s[16:17], 0, v[110:111]
	v_lshl_add_u64 v[110:111], v[110:111], 0, v[116:117]
	global_load_dwordx4 v[110:113], v[110:111], off
	s_waitcnt lgkmcnt(4)
	v_ashrrev_i32_e32 v121, 31, v120
	v_lshlrev_b64 v[120:121], 10, v[120:121]
	v_lshl_add_u64 v[120:121], s[16:17], 0, v[120:121]
	v_lshl_add_u64 v[120:121], v[120:121], 0, v[126:127]
	global_load_dwordx4 v[120:123], v[120:121], off
	s_waitcnt lgkmcnt(3)
	v_ashrrev_i32_e32 v131, 31, v130
	v_lshlrev_b64 v[130:131], 10, v[130:131]
	v_lshl_add_u64 v[130:131], s[16:17], 0, v[130:131]
	v_lshl_add_u64 v[130:131], v[130:131], 0, v[136:137]
	global_load_dwordx4 v[130:133], v[130:131], off
	s_waitcnt lgkmcnt(2)
	v_ashrrev_i32_e32 v155, 31, v154
	v_lshlrev_b64 v[154:155], 10, v[154:155]
	v_lshl_add_u64 v[154:155], s[16:17], 0, v[154:155]
	v_lshl_add_u64 v[154:155], v[154:155], 0, v[160:161]
	global_load_dwordx4 v[154:157], v[154:155], off
	s_waitcnt lgkmcnt(1)
	v_ashrrev_i32_e32 v165, 31, v164
	v_lshlrev_b64 v[164:165], 10, v[164:165]
	v_lshl_add_u64 v[164:165], s[16:17], 0, v[164:165]
	v_lshl_add_u64 v[164:165], v[164:165], 0, v[170:171]
	global_load_dwordx4 v[164:167], v[164:165], off
	s_waitcnt lgkmcnt(0)
	v_ashrrev_i32_e32 v207, 31, v206
	v_lshlrev_b64 v[206:207], 10, v[206:207]
	v_lshl_add_u64 v[206:207], s[16:17], 0, v[206:207]
	v_lshl_add_u64 v[206:207], v[206:207], 0, v[212:213]
	global_load_dwordx4 v[206:209], v[206:207], off
	s_waitcnt vmcnt(7)
	ds_write2_b32 v94, v90, v91 offset1:68
	ds_write2_b32 v94, v92, v93 offset0:136 offset1:204
	s_waitcnt vmcnt(6)
	ds_write2_b32 v104, v100, v101 offset1:68
	ds_write2_b32 v104, v102, v103 offset0:136 offset1:204
	s_waitcnt vmcnt(5)
	ds_write2_b32 v114, v110, v111 offset1:68
	ds_write2_b32 v114, v112, v113 offset0:136 offset1:204
	s_waitcnt vmcnt(4)
	ds_write2_b32 v124, v120, v121 offset1:68
	ds_write2_b32 v124, v122, v123 offset0:136 offset1:204
	s_waitcnt vmcnt(3)
	ds_write2_b32 v134, v130, v131 offset1:68
	ds_write2_b32 v134, v132, v133 offset0:136 offset1:204
	s_waitcnt vmcnt(2)
	ds_write2_b32 v158, v154, v155 offset1:68
	ds_write2_b32 v158, v156, v157 offset0:136 offset1:204
	s_waitcnt vmcnt(1)
	ds_write2_b32 v168, v164, v165 offset1:68
	ds_write2_b32 v168, v166, v167 offset0:136 offset1:204
	s_waitcnt vmcnt(0)
	ds_write2_b32 v210, v206, v207 offset1:68
	ds_write2_b32 v210, v208, v209 offset0:136 offset1:204
